# merge step epilogues batched (all loads first, counted vmcnt) on top of all-DMA merge
# speedup vs baseline: 1.0024x; 1.0024x over previous
.LBB0_241:
	s_setprio 1
	ds_read_b128 v[120:123], v117 offset:16384
	ds_read_b128 v[124:127], v119
	ds_read_b128 v[140:143], v117 offset:18432
	ds_read_b128 v[160:163], v117 offset:20480
	ds_read_b128 v[164:167], v117 offset:22528
	ds_read_b128 v[132:135], v119 offset:2048
	ds_read_b128 v[152:155], v119 offset:4096
	ds_read_b128 v[156:159], v119 offset:6144
	v_lshrrev_b32_e32 v30, 3, v169
	v_and_b32_e32 v31, 3, v30
	v_bfe_u32 v32, v30, 4, 1
	v_lshl_or_b32 v31, v32, 2, v31
	v_bfe_u32 v32, v30, 2, 1
	v_lshl_or_b32 v31, v32, 3, v31
	v_bfe_u32 v32, v30, 3, 1
	v_lshl_or_b32 v31, v32, 4, v31
	v_sub_u32_e32 v31, v31, v30
	v_and_b32_e32 v30, 7, v30
	v_mul_i32_i24_e32 v31, s101, v31
	v_lshlrev_b32_e32 v30, 3, v30
	v_xor_b32_e32 v0, v0, v30
	v_add_u32_e32 v110, v110, v31
	v_xor_b32_e32 v110, v110, v30
	v_xor_b32_e32 v104, v104, v30
	v_add_u32_e32 v108, v108, v31
	v_xor_b32_e32 v108, v108, v30
	v_xor_b32_e32 v100, v100, v30
	v_add_u32_e32 v106, v106, v31
	v_xor_b32_e32 v106, v106, v30
	v_xor_b32_e32 v98, v98, v30
	v_add_u32_e32 v102, v102, v31
	v_xor_b32_e32 v102, v102, v30
	v_mov_b32_e32 v111, v1
	v_mov_b32_e32 v105, v1
	v_mov_b32_e32 v109, v1
	v_mov_b32_e32 v101, v1
	v_mov_b32_e32 v107, v1
	v_mov_b32_e32 v99, v1
	v_mov_b32_e32 v103, v1
	v_lshl_add_u64 v[128:129], v[0:1], 1, s[34:35]
	v_lshl_add_u64 v[136:137], v[110:111], 1, s[28:29]
	v_lshl_add_u64 v[144:145], v[104:105], 1, s[34:35]
	v_lshl_add_u64 v[174:175], v[108:109], 1, s[28:29]
	v_lshl_add_u64 v[176:177], v[100:101], 1, s[34:35]
	v_lshl_add_u64 v[178:179], v[106:107], 1, s[28:29]
	v_lshl_add_u64 v[180:181], v[98:99], 1, s[34:35]
	v_lshl_add_u64 v[186:187], v[102:103], 1, s[28:29]
	s_add_u32 m0, s100, 0x8000
	s_waitcnt lgkmcnt(6)
	v_mfma_f32_16x16x32_bf16 v[194:197], v[120:123], v[124:127], v[34:37]
	global_load_lds_dwordx4 v[2:3], off
	s_waitcnt lgkmcnt(5)
	v_mfma_f32_16x16x32_bf16 v[94:97], v[140:143], v[124:127], v[94:97]
	ds_read_b128 v[198:201], v118
	s_add_u32 m0, s100, 0xc000
	s_waitcnt lgkmcnt(5)
	v_mfma_f32_16x16x32_bf16 v[202:205], v[160:163], v[124:127], v[38:41]
	global_load_lds_dwordx4 v[4:5], off
	s_waitcnt lgkmcnt(4)
	v_mfma_f32_16x16x32_bf16 v[90:93], v[164:167], v[124:127], v[90:93]
	ds_read_b128 v[110:113], v118 offset:2048
	s_add_u32 m0, s100, 0x9000
	s_waitcnt lgkmcnt(4)
	v_mfma_f32_16x16x32_bf16 v[124:127], v[120:123], v[132:135], v[42:45]
	global_load_lds_dwordx4 v[6:7], off
	v_mfma_f32_16x16x32_bf16 v[86:89], v[140:143], v[132:135], v[86:89]
	ds_read_b128 v[206:209], v118 offset:4096
	s_add_u32 m0, s100, 0xd000
	v_mfma_f32_16x16x32_bf16 v[210:213], v[160:163], v[132:135], v[46:49]
	global_load_lds_dwordx4 v[8:9], off
	v_mfma_f32_16x16x32_bf16 v[82:85], v[164:167], v[132:135], v[82:85]
	ds_read_b128 v[132:135], v118 offset:6144
	s_add_u32 m0, s100, 0xa000
	s_waitcnt lgkmcnt(5)
	v_mfma_f32_16x16x32_bf16 v[214:217], v[120:123], v[152:155], v[50:53]
	global_load_lds_dwordx4 v[14:15], off
	v_mfma_f32_16x16x32_bf16 v[78:81], v[140:143], v[152:155], v[78:81]
	ds_read_b128 v[218:221], v130 offset:16384
	s_add_u32 m0, s100, 0xe000
	v_mfma_f32_16x16x32_bf16 v[222:225], v[160:163], v[152:155], v[54:57]
	global_load_lds_dwordx4 v[16:17], off
	v_mfma_f32_16x16x32_bf16 v[70:73], v[164:167], v[152:155], v[70:73]
	ds_read_b128 v[104:107], v130 offset:18432
	s_add_u32 m0, s100, 0xb000
	s_waitcnt lgkmcnt(6)
	v_mfma_f32_16x16x32_bf16 v[120:123], v[120:123], v[156:159], v[58:61]
	global_load_lds_dwordx4 v[22:23], off
	v_mfma_f32_16x16x32_bf16 v[66:69], v[140:143], v[156:159], v[66:69]
	ds_read_b128 v[98:101], v130 offset:20480
	s_add_u32 m0, s100, 0xf000
	v_mfma_f32_16x16x32_bf16 v[140:143], v[160:163], v[156:159], v[62:65]
	global_load_lds_dwordx4 v[24:25], off
	v_mfma_f32_16x16x32_bf16 v[74:77], v[164:167], v[156:159], v[74:77]
	ds_read_b128 v[152:155], v130 offset:22528
	s_waitcnt lgkmcnt(3)
	v_mfma_f32_16x16x32_bf16 v[156:159], v[218:221], v[198:201], v[194:197]
	s_waitcnt lgkmcnt(2)
	v_mfma_f32_16x16x32_bf16 v[94:97], v[104:107], v[198:201], v[94:97]
	s_waitcnt lgkmcnt(1)
	v_mfma_f32_16x16x32_bf16 v[160:163], v[98:101], v[198:201], v[202:205]
	s_waitcnt lgkmcnt(0)
	v_mfma_f32_16x16x32_bf16 v[90:93], v[152:155], v[198:201], v[90:93]
	v_mfma_f32_16x16x32_bf16 v[124:127], v[218:221], v[110:113], v[124:127]
	v_mfma_f32_16x16x32_bf16 v[86:89], v[104:107], v[110:113], v[86:89]
	v_mfma_f32_16x16x32_bf16 v[164:167], v[98:101], v[110:113], v[210:213]
	v_mfma_f32_16x16x32_bf16 v[82:85], v[152:155], v[110:113], v[82:85]
	v_mfma_f32_16x16x32_bf16 v[108:111], v[218:221], v[206:209], v[214:217]
	v_mfma_f32_16x16x32_bf16 v[78:81], v[104:107], v[206:209], v[78:81]
	v_mfma_f32_16x16x32_bf16 v[194:197], v[98:101], v[206:209], v[222:225]
	v_mfma_f32_16x16x32_bf16 v[70:73], v[152:155], v[206:209], v[70:73]
	v_mfma_f32_16x16x32_bf16 v[120:123], v[218:221], v[132:135], v[120:123]
	v_mfma_f32_16x16x32_bf16 v[66:69], v[104:107], v[132:135], v[66:69]
	v_mfma_f32_16x16x32_bf16 v[98:101], v[98:101], v[132:135], v[140:143]
	v_mfma_f32_16x16x32_bf16 v[74:77], v[152:155], v[132:135], v[74:77]
	s_waitcnt vmcnt(0)
	s_setprio 0
	s_waitcnt lgkmcnt(0)
	s_barrier
	s_setprio 1
	ds_read_b128 v[26:29], v117 offset:49152
	ds_read_b128 v[10:13], v119 offset:32768
	ds_read_b128 v[30:33], v117 offset:51200
	ds_read_b128 v[132:135], v117 offset:53248
	ds_read_b128 v[140:143], v117 offset:55296
	ds_read_b128 v[18:21], v119 offset:34816
	ds_read_b128 v[102:105], v119 offset:36864
	ds_read_b128 v[112:115], v119 offset:38912
	s_add_u32 m0, s100, 0x0
	s_waitcnt lgkmcnt(6)
	v_mfma_f32_16x16x32_bf16 v[152:155], v[26:29], v[10:13], v[156:159]
	global_load_lds_dwordx4 v[128:129], off
	s_waitcnt lgkmcnt(5)
	v_mfma_f32_16x16x32_bf16 v[94:97], v[30:33], v[10:13], v[94:97]
	ds_read_b128 v[156:159], v118 offset:32768
	s_add_u32 m0, s100, 0x4000
	s_waitcnt lgkmcnt(5)
	v_mfma_f32_16x16x32_bf16 v[160:163], v[132:135], v[10:13], v[160:163]
	global_load_lds_dwordx4 v[136:137], off
	s_waitcnt lgkmcnt(4)
	v_mfma_f32_16x16x32_bf16 v[90:93], v[140:143], v[10:13], v[90:93]
	ds_read_b128 v[198:201], v118 offset:34816
	s_add_u32 m0, s100, 0x1000
	s_waitcnt lgkmcnt(4)
	v_mfma_f32_16x16x32_bf16 v[202:205], v[26:29], v[18:21], v[124:127]
	global_load_lds_dwordx4 v[144:145], off
	v_mfma_f32_16x16x32_bf16 v[86:89], v[30:33], v[18:21], v[86:89]
	ds_read_b128 v[206:209], v118 offset:36864
	s_add_u32 m0, s100, 0x5000
	v_mfma_f32_16x16x32_bf16 v[164:167], v[132:135], v[18:21], v[164:167]
	global_load_lds_dwordx4 v[174:175], off
	v_mfma_f32_16x16x32_bf16 v[82:85], v[140:143], v[18:21], v[82:85]
	ds_read_b128 v[210:213], v118 offset:38912
	s_add_u32 m0, s100, 0x2000
	s_waitcnt lgkmcnt(5)
	v_mfma_f32_16x16x32_bf16 v[214:217], v[26:29], v[102:105], v[108:111]
	global_load_lds_dwordx4 v[176:177], off
	v_mfma_f32_16x16x32_bf16 v[78:81], v[30:33], v[102:105], v[78:81]
	ds_read_b128 v[218:221], v130 offset:49152
	s_add_u32 m0, s100, 0x6000
	v_mfma_f32_16x16x32_bf16 v[194:197], v[132:135], v[102:105], v[194:197]
	global_load_lds_dwordx4 v[178:179], off
	v_mfma_f32_16x16x32_bf16 v[70:73], v[140:143], v[102:105], v[70:73]
	ds_read_b128 v[222:225], v130 offset:51200
	s_add_u32 m0, s100, 0x3000
	s_waitcnt lgkmcnt(6)
	v_mfma_f32_16x16x32_bf16 v[226:229], v[26:29], v[112:115], v[120:123]
	global_load_lds_dwordx4 v[180:181], off
	v_mfma_f32_16x16x32_bf16 v[66:69], v[30:33], v[112:115], v[66:69]
	ds_read_b128 v[230:233], v130 offset:53248
	s_add_u32 m0, s100, 0x7000
	v_mfma_f32_16x16x32_bf16 v[132:135], v[132:135], v[112:115], v[98:101]
	global_load_lds_dwordx4 v[186:187], off
	v_mfma_f32_16x16x32_bf16 v[140:143], v[140:143], v[112:115], v[74:77]
	s_waitcnt lgkmcnt(2)
	v_mfma_f32_16x16x32_bf16 v[126:129], v[218:221], v[156:159], v[152:155]
	ds_read_b128 v[152:155], v130 offset:55296
	s_waitcnt lgkmcnt(2)
	v_mfma_f32_16x16x32_bf16 v[122:125], v[222:225], v[156:159], v[94:97]
	s_waitcnt lgkmcnt(1)
	v_mfma_f32_16x16x32_bf16 v[118:121], v[230:233], v[156:159], v[160:163]
	s_waitcnt lgkmcnt(0)
	v_mfma_f32_16x16x32_bf16 v[114:117], v[152:155], v[156:159], v[90:93]
	v_mfma_f32_16x16x32_bf16 v[110:113], v[218:221], v[198:201], v[202:205]
	v_mfma_f32_16x16x32_bf16 v[106:109], v[222:225], v[198:201], v[86:89]
	v_mfma_f32_16x16x32_bf16 v[102:105], v[230:233], v[198:201], v[164:167]
	v_mfma_f32_16x16x32_bf16 v[98:101], v[152:155], v[198:201], v[82:85]
	v_mfma_f32_16x16x32_bf16 v[94:97], v[218:221], v[206:209], v[214:217]
	v_mfma_f32_16x16x32_bf16 v[90:93], v[222:225], v[206:209], v[78:81]
	v_mfma_f32_16x16x32_bf16 v[86:89], v[230:233], v[206:209], v[194:197]
	v_mfma_f32_16x16x32_bf16 v[82:85], v[152:155], v[206:209], v[70:73]
	v_mfma_f32_16x16x32_bf16 v[78:81], v[218:221], v[210:213], v[226:229]
	v_mfma_f32_16x16x32_bf16 v[74:77], v[222:225], v[210:213], v[66:69]
	v_mfma_f32_16x16x32_bf16 v[66:69], v[230:233], v[210:213], v[132:135]
	v_mfma_f32_16x16x32_bf16 v[70:73], v[152:155], v[210:213], v[140:143]
	s_setprio 0
	s_barrier
	s_cmp_eq_u32 s9, 0
	s_cbranch_scc1 .Lme_s0
	s_cmp_eq_u32 s9, 1
	s_cbranch_scc1 .Lme_s1
	v_or_b32_e32 v0, s2, v147
	v_add_u32_e32 v140, s25, v146
	v_ashrrev_i32_e32 v141, 31, v140
	v_lshlrev_b64 v[140:141], 11, v[140:141]
	v_lshl_add_u64 v[140:141], v[0:1], 1, v[140:141]
	v_lshl_add_u64 v[130:131], v[140:141], 0, s[46:47]
	v_lshl_add_u64 v[142:143], v[140:141], 0, s[40:41]
	global_load_dwordx4 v[2:5], v[130:131], off
	global_load_dwordx4 v[34:37], v[142:143], off
	global_load_dwordx4 v[6:9], v[130:131], off offset:64
	global_load_dwordx4 v[38:41], v[142:143], off offset:64
	v_add_u32_e32 v140, s25, v148
	v_ashrrev_i32_e32 v141, 31, v140
	v_lshlrev_b64 v[140:141], 11, v[140:141]
	v_lshl_add_u64 v[140:141], v[0:1], 1, v[140:141]
	v_lshl_add_u64 v[132:133], v[140:141], 0, s[46:47]
	v_lshl_add_u64 v[142:143], v[140:141], 0, s[40:41]
	global_load_dwordx4 v[10:13], v[132:133], off
	global_load_dwordx4 v[42:45], v[142:143], off
	global_load_dwordx4 v[14:17], v[132:133], off offset:64
	global_load_dwordx4 v[46:49], v[142:143], off offset:64
	v_add_u32_e32 v140, s25, v149
	v_ashrrev_i32_e32 v141, 31, v140
	v_lshlrev_b64 v[140:141], 11, v[140:141]
	v_lshl_add_u64 v[140:141], v[0:1], 1, v[140:141]
	v_lshl_add_u64 v[134:135], v[140:141], 0, s[46:47]
	v_lshl_add_u64 v[142:143], v[140:141], 0, s[40:41]
	global_load_dwordx4 v[18:21], v[134:135], off
	global_load_dwordx4 v[50:53], v[142:143], off
	global_load_dwordx4 v[22:25], v[134:135], off offset:64
	global_load_dwordx4 v[54:57], v[142:143], off offset:64
	v_add_u32_e32 v140, s25, v150
	v_ashrrev_i32_e32 v141, 31, v140
	v_lshlrev_b64 v[140:141], 11, v[140:141]
	v_lshl_add_u64 v[140:141], v[0:1], 1, v[140:141]
	v_lshl_add_u64 v[136:137], v[140:141], 0, s[46:47]
	v_lshl_add_u64 v[142:143], v[140:141], 0, s[40:41]
	global_load_dwordx4 v[26:29], v[136:137], off
	global_load_dwordx4 v[58:61], v[142:143], off
	global_load_dwordx4 v[30:33], v[136:137], off offset:64
	global_load_dwordx4 v[62:65], v[142:143], off offset:64
	v_mul_f32_e32 v126, 0xbfb8aa3b, v126
	v_mul_f32_e32 v127, 0xbfb8aa3b, v127
	v_mul_f32_e32 v128, 0xbfb8aa3b, v128
	v_mul_f32_e32 v129, 0xbfb8aa3b, v129
	v_mul_f32_e32 v122, 0xbfb8aa3b, v122
	v_mul_f32_e32 v123, 0xbfb8aa3b, v123
	v_mul_f32_e32 v124, 0xbfb8aa3b, v124
	v_mul_f32_e32 v125, 0xbfb8aa3b, v125
	v_exp_f32_e32 v126, v126
	v_exp_f32_e32 v127, v127
	v_exp_f32_e32 v128, v128
	v_exp_f32_e32 v129, v129
	v_exp_f32_e32 v122, v122
	v_exp_f32_e32 v123, v123
	v_exp_f32_e32 v124, v124
	v_exp_f32_e32 v125, v125
	v_add_f32_e32 v126, 1.0, v126
	v_add_f32_e32 v127, 1.0, v127
	v_add_f32_e32 v128, 1.0, v128
	v_add_f32_e32 v129, 1.0, v129
	v_add_f32_e32 v122, 1.0, v122
	v_add_f32_e32 v123, 1.0, v123
	v_add_f32_e32 v124, 1.0, v124
	v_add_f32_e32 v125, 1.0, v125
	v_rcp_f32_e32 v126, v126
	v_rcp_f32_e32 v127, v127
	v_rcp_f32_e32 v128, v128
	v_rcp_f32_e32 v129, v129
	v_rcp_f32_e32 v122, v122
	v_rcp_f32_e32 v123, v123
	v_rcp_f32_e32 v124, v124
	v_rcp_f32_e32 v125, v125
	v_mul_f32_e32 v118, 0xbfb8aa3b, v118
	v_mul_f32_e32 v119, 0xbfb8aa3b, v119
	v_mul_f32_e32 v120, 0xbfb8aa3b, v120
	v_mul_f32_e32 v121, 0xbfb8aa3b, v121
	v_mul_f32_e32 v114, 0xbfb8aa3b, v114
	v_mul_f32_e32 v115, 0xbfb8aa3b, v115
	v_mul_f32_e32 v116, 0xbfb8aa3b, v116
	v_mul_f32_e32 v117, 0xbfb8aa3b, v117
	v_exp_f32_e32 v118, v118
	v_exp_f32_e32 v119, v119
	v_exp_f32_e32 v120, v120
	v_exp_f32_e32 v121, v121
	v_exp_f32_e32 v114, v114
	v_exp_f32_e32 v115, v115
	v_exp_f32_e32 v116, v116
	v_exp_f32_e32 v117, v117
	v_add_f32_e32 v118, 1.0, v118
	v_add_f32_e32 v119, 1.0, v119
	v_add_f32_e32 v120, 1.0, v120
	v_add_f32_e32 v121, 1.0, v121
	v_add_f32_e32 v114, 1.0, v114
	v_add_f32_e32 v115, 1.0, v115
	v_add_f32_e32 v116, 1.0, v116
	v_add_f32_e32 v117, 1.0, v117
	v_rcp_f32_e32 v118, v118
	v_rcp_f32_e32 v119, v119
	v_rcp_f32_e32 v120, v120
	v_rcp_f32_e32 v121, v121
	v_rcp_f32_e32 v114, v114
	v_rcp_f32_e32 v115, v115
	v_rcp_f32_e32 v116, v116
	v_rcp_f32_e32 v117, v117
	v_mul_f32_e32 v110, 0xbfb8aa3b, v110
	v_mul_f32_e32 v111, 0xbfb8aa3b, v111
	v_mul_f32_e32 v112, 0xbfb8aa3b, v112
	v_mul_f32_e32 v113, 0xbfb8aa3b, v113
	v_mul_f32_e32 v106, 0xbfb8aa3b, v106
	v_mul_f32_e32 v107, 0xbfb8aa3b, v107
	v_mul_f32_e32 v108, 0xbfb8aa3b, v108
	v_mul_f32_e32 v109, 0xbfb8aa3b, v109
	v_exp_f32_e32 v110, v110
	v_exp_f32_e32 v111, v111
	v_exp_f32_e32 v112, v112
	v_exp_f32_e32 v113, v113
	v_exp_f32_e32 v106, v106
	v_exp_f32_e32 v107, v107
	v_exp_f32_e32 v108, v108
	v_exp_f32_e32 v109, v109
	v_add_f32_e32 v110, 1.0, v110
	v_add_f32_e32 v111, 1.0, v111
	v_add_f32_e32 v112, 1.0, v112
	v_add_f32_e32 v113, 1.0, v113
	v_add_f32_e32 v106, 1.0, v106
	v_add_f32_e32 v107, 1.0, v107
	v_add_f32_e32 v108, 1.0, v108
	v_add_f32_e32 v109, 1.0, v109
	v_rcp_f32_e32 v110, v110
	v_rcp_f32_e32 v111, v111
	v_rcp_f32_e32 v112, v112
	v_rcp_f32_e32 v113, v113
	v_rcp_f32_e32 v106, v106
	v_rcp_f32_e32 v107, v107
	v_rcp_f32_e32 v108, v108
	v_rcp_f32_e32 v109, v109
	v_mul_f32_e32 v102, 0xbfb8aa3b, v102
	v_mul_f32_e32 v103, 0xbfb8aa3b, v103
	v_mul_f32_e32 v104, 0xbfb8aa3b, v104
	v_mul_f32_e32 v105, 0xbfb8aa3b, v105
	v_mul_f32_e32 v98, 0xbfb8aa3b, v98
	v_mul_f32_e32 v99, 0xbfb8aa3b, v99
	v_mul_f32_e32 v100, 0xbfb8aa3b, v100
	v_mul_f32_e32 v101, 0xbfb8aa3b, v101
	v_exp_f32_e32 v102, v102
	v_exp_f32_e32 v103, v103
	v_exp_f32_e32 v104, v104
	v_exp_f32_e32 v105, v105
	v_exp_f32_e32 v98, v98
	v_exp_f32_e32 v99, v99
	v_exp_f32_e32 v100, v100
	v_exp_f32_e32 v101, v101
	v_add_f32_e32 v102, 1.0, v102
	v_add_f32_e32 v103, 1.0, v103
	v_add_f32_e32 v104, 1.0, v104
	v_add_f32_e32 v105, 1.0, v105
	v_add_f32_e32 v98, 1.0, v98
	v_add_f32_e32 v99, 1.0, v99
	v_add_f32_e32 v100, 1.0, v100
	v_add_f32_e32 v101, 1.0, v101
	v_rcp_f32_e32 v102, v102
	v_rcp_f32_e32 v103, v103
	v_rcp_f32_e32 v104, v104
	v_rcp_f32_e32 v105, v105
	v_rcp_f32_e32 v98, v98
	v_rcp_f32_e32 v99, v99
	v_rcp_f32_e32 v100, v100
	v_rcp_f32_e32 v101, v101
	v_mul_f32_e32 v94, 0xbfb8aa3b, v94
	v_mul_f32_e32 v95, 0xbfb8aa3b, v95
	v_mul_f32_e32 v96, 0xbfb8aa3b, v96
	v_mul_f32_e32 v97, 0xbfb8aa3b, v97
	v_mul_f32_e32 v90, 0xbfb8aa3b, v90
	v_mul_f32_e32 v91, 0xbfb8aa3b, v91
	v_mul_f32_e32 v92, 0xbfb8aa3b, v92
	v_mul_f32_e32 v93, 0xbfb8aa3b, v93
	v_exp_f32_e32 v94, v94
	v_exp_f32_e32 v95, v95
	v_exp_f32_e32 v96, v96
	v_exp_f32_e32 v97, v97
	v_exp_f32_e32 v90, v90
	v_exp_f32_e32 v91, v91
	v_exp_f32_e32 v92, v92
	v_exp_f32_e32 v93, v93
	v_add_f32_e32 v94, 1.0, v94
	v_add_f32_e32 v95, 1.0, v95
	v_add_f32_e32 v96, 1.0, v96
	v_add_f32_e32 v97, 1.0, v97
	v_add_f32_e32 v90, 1.0, v90
	v_add_f32_e32 v91, 1.0, v91
	v_add_f32_e32 v92, 1.0, v92
	v_add_f32_e32 v93, 1.0, v93
	v_rcp_f32_e32 v94, v94
	v_rcp_f32_e32 v95, v95
	v_rcp_f32_e32 v96, v96
	v_rcp_f32_e32 v97, v97
	v_rcp_f32_e32 v90, v90
	v_rcp_f32_e32 v91, v91
	v_rcp_f32_e32 v92, v92
	v_rcp_f32_e32 v93, v93
	v_mul_f32_e32 v86, 0xbfb8aa3b, v86
	v_mul_f32_e32 v87, 0xbfb8aa3b, v87
	v_mul_f32_e32 v88, 0xbfb8aa3b, v88
	v_mul_f32_e32 v89, 0xbfb8aa3b, v89
	v_mul_f32_e32 v82, 0xbfb8aa3b, v82
	v_mul_f32_e32 v83, 0xbfb8aa3b, v83
	v_mul_f32_e32 v84, 0xbfb8aa3b, v84
	v_mul_f32_e32 v85, 0xbfb8aa3b, v85
	v_exp_f32_e32 v86, v86
	v_exp_f32_e32 v87, v87
	v_exp_f32_e32 v88, v88
	v_exp_f32_e32 v89, v89
	v_exp_f32_e32 v82, v82
	v_exp_f32_e32 v83, v83
	v_exp_f32_e32 v84, v84
	v_exp_f32_e32 v85, v85
	v_add_f32_e32 v86, 1.0, v86
	v_add_f32_e32 v87, 1.0, v87
	v_add_f32_e32 v88, 1.0, v88
	v_add_f32_e32 v89, 1.0, v89
	v_add_f32_e32 v82, 1.0, v82
	v_add_f32_e32 v83, 1.0, v83
	v_add_f32_e32 v84, 1.0, v84
	v_add_f32_e32 v85, 1.0, v85
	v_rcp_f32_e32 v86, v86
	v_rcp_f32_e32 v87, v87
	v_rcp_f32_e32 v88, v88
	v_rcp_f32_e32 v89, v89
	v_rcp_f32_e32 v82, v82
	v_rcp_f32_e32 v83, v83
	v_rcp_f32_e32 v84, v84
	v_rcp_f32_e32 v85, v85
	v_mul_f32_e32 v78, 0xbfb8aa3b, v78
	v_mul_f32_e32 v79, 0xbfb8aa3b, v79
	v_mul_f32_e32 v80, 0xbfb8aa3b, v80
	v_mul_f32_e32 v81, 0xbfb8aa3b, v81
	v_mul_f32_e32 v74, 0xbfb8aa3b, v74
	v_mul_f32_e32 v75, 0xbfb8aa3b, v75
	v_mul_f32_e32 v76, 0xbfb8aa3b, v76
	v_mul_f32_e32 v77, 0xbfb8aa3b, v77
	v_exp_f32_e32 v78, v78
	v_exp_f32_e32 v79, v79
	v_exp_f32_e32 v80, v80
	v_exp_f32_e32 v81, v81
	v_exp_f32_e32 v74, v74
	v_exp_f32_e32 v75, v75
	v_exp_f32_e32 v76, v76
	v_exp_f32_e32 v77, v77
	v_add_f32_e32 v78, 1.0, v78
	v_add_f32_e32 v79, 1.0, v79
	v_add_f32_e32 v80, 1.0, v80
	v_add_f32_e32 v81, 1.0, v81
	v_add_f32_e32 v74, 1.0, v74
	v_add_f32_e32 v75, 1.0, v75
	v_add_f32_e32 v76, 1.0, v76
	v_add_f32_e32 v77, 1.0, v77
	v_rcp_f32_e32 v78, v78
	v_rcp_f32_e32 v79, v79
	v_rcp_f32_e32 v80, v80
	v_rcp_f32_e32 v81, v81
	v_rcp_f32_e32 v74, v74
	v_rcp_f32_e32 v75, v75
	v_rcp_f32_e32 v76, v76
	v_rcp_f32_e32 v77, v77
	v_mul_f32_e32 v66, 0xbfb8aa3b, v66
	v_mul_f32_e32 v67, 0xbfb8aa3b, v67
	v_mul_f32_e32 v68, 0xbfb8aa3b, v68
	v_mul_f32_e32 v69, 0xbfb8aa3b, v69
	v_mul_f32_e32 v70, 0xbfb8aa3b, v70
	v_mul_f32_e32 v71, 0xbfb8aa3b, v71
	v_mul_f32_e32 v72, 0xbfb8aa3b, v72
	v_mul_f32_e32 v73, 0xbfb8aa3b, v73
	v_exp_f32_e32 v66, v66
	v_exp_f32_e32 v67, v67
	v_exp_f32_e32 v68, v68
	v_exp_f32_e32 v69, v69
	v_exp_f32_e32 v70, v70
	v_exp_f32_e32 v71, v71
	v_exp_f32_e32 v72, v72
	v_exp_f32_e32 v73, v73
	v_add_f32_e32 v66, 1.0, v66
	v_add_f32_e32 v67, 1.0, v67
	v_add_f32_e32 v68, 1.0, v68
	v_add_f32_e32 v69, 1.0, v69
	v_add_f32_e32 v70, 1.0, v70
	v_add_f32_e32 v71, 1.0, v71
	v_add_f32_e32 v72, 1.0, v72
	v_add_f32_e32 v73, 1.0, v73
	v_rcp_f32_e32 v66, v66
	v_rcp_f32_e32 v67, v67
	v_rcp_f32_e32 v68, v68
	v_rcp_f32_e32 v69, v69
	v_rcp_f32_e32 v70, v70
	v_rcp_f32_e32 v71, v71
	v_rcp_f32_e32 v72, v72
	v_rcp_f32_e32 v73, v73
	s_nop 0
	s_waitcnt vmcnt(14)
	v_lshlrev_b32_e32 v140, 16, v2
	v_and_b32_e32 v141, 0xffff0000, v2
	v_lshlrev_b32_e32 v142, 16, v34
	v_and_b32_e32 v143, 0xffff0000, v34
	v_pk_fma_f32 v[126:127], v[126:127], v[142:143], v[140:141]
	v_lshlrev_b32_e32 v144, 16, v3
	v_and_b32_e32 v145, 0xffff0000, v3
	v_lshlrev_b32_e32 v152, 16, v35
	v_and_b32_e32 v153, 0xffff0000, v35
	v_pk_fma_f32 v[128:129], v[128:129], v[152:153], v[144:145]
	v_lshlrev_b32_e32 v140, 16, v4
	v_and_b32_e32 v141, 0xffff0000, v4
	v_lshlrev_b32_e32 v142, 16, v36
	v_and_b32_e32 v143, 0xffff0000, v36
	v_pk_fma_f32 v[122:123], v[122:123], v[142:143], v[140:141]
	v_lshlrev_b32_e32 v144, 16, v5
	v_and_b32_e32 v145, 0xffff0000, v5
	v_lshlrev_b32_e32 v152, 16, v37
	v_and_b32_e32 v153, 0xffff0000, v37
	v_pk_fma_f32 v[124:125], v[124:125], v[152:153], v[144:145]
	v_cvt_pk_bf16_f32 v125, v124, v125
	v_cvt_pk_bf16_f32 v124, v122, v123
	v_cvt_pk_bf16_f32 v122, v126, v127
	v_cvt_pk_bf16_f32 v123, v128, v129
	global_store_dwordx4 v[130:131], v[122:125], off
	s_waitcnt vmcnt(13)
	v_lshlrev_b32_e32 v140, 16, v6
	v_and_b32_e32 v141, 0xffff0000, v6
	v_lshlrev_b32_e32 v142, 16, v38
	v_and_b32_e32 v143, 0xffff0000, v38
	v_pk_fma_f32 v[118:119], v[118:119], v[142:143], v[140:141]
	v_lshlrev_b32_e32 v144, 16, v7
	v_and_b32_e32 v145, 0xffff0000, v7
	v_lshlrev_b32_e32 v152, 16, v39
	v_and_b32_e32 v153, 0xffff0000, v39
	v_pk_fma_f32 v[120:121], v[120:121], v[152:153], v[144:145]
	v_lshlrev_b32_e32 v140, 16, v8
	v_and_b32_e32 v141, 0xffff0000, v8
	v_lshlrev_b32_e32 v142, 16, v40
	v_and_b32_e32 v143, 0xffff0000, v40
	v_pk_fma_f32 v[114:115], v[114:115], v[142:143], v[140:141]
	v_lshlrev_b32_e32 v144, 16, v9
	v_and_b32_e32 v145, 0xffff0000, v9
	v_lshlrev_b32_e32 v152, 16, v41
	v_and_b32_e32 v153, 0xffff0000, v41
	v_pk_fma_f32 v[116:117], v[116:117], v[152:153], v[144:145]
	v_cvt_pk_bf16_f32 v117, v116, v117
	v_cvt_pk_bf16_f32 v116, v114, v115
	v_cvt_pk_bf16_f32 v114, v118, v119
	v_cvt_pk_bf16_f32 v115, v120, v121
	global_store_dwordx4 v[130:131], v[114:117], off offset:64
	s_waitcnt vmcnt(12)
	v_lshlrev_b32_e32 v140, 16, v10
	v_and_b32_e32 v141, 0xffff0000, v10
	v_lshlrev_b32_e32 v142, 16, v42
	v_and_b32_e32 v143, 0xffff0000, v42
	v_pk_fma_f32 v[110:111], v[110:111], v[142:143], v[140:141]
	v_lshlrev_b32_e32 v144, 16, v11
	v_and_b32_e32 v145, 0xffff0000, v11
	v_lshlrev_b32_e32 v152, 16, v43
	v_and_b32_e32 v153, 0xffff0000, v43
	v_pk_fma_f32 v[112:113], v[112:113], v[152:153], v[144:145]
	v_lshlrev_b32_e32 v140, 16, v12
	v_and_b32_e32 v141, 0xffff0000, v12
	v_lshlrev_b32_e32 v142, 16, v44
	v_and_b32_e32 v143, 0xffff0000, v44
	v_pk_fma_f32 v[106:107], v[106:107], v[142:143], v[140:141]
	v_lshlrev_b32_e32 v144, 16, v13
	v_and_b32_e32 v145, 0xffff0000, v13
	v_lshlrev_b32_e32 v152, 16, v45
	v_and_b32_e32 v153, 0xffff0000, v45
	v_pk_fma_f32 v[108:109], v[108:109], v[152:153], v[144:145]
	v_cvt_pk_bf16_f32 v109, v108, v109
	v_cvt_pk_bf16_f32 v108, v106, v107
	v_cvt_pk_bf16_f32 v106, v110, v111
	v_cvt_pk_bf16_f32 v107, v112, v113
	global_store_dwordx4 v[132:133], v[106:109], off
	s_waitcnt vmcnt(11)
	v_lshlrev_b32_e32 v140, 16, v14
	v_and_b32_e32 v141, 0xffff0000, v14
	v_lshlrev_b32_e32 v142, 16, v46
	v_and_b32_e32 v143, 0xffff0000, v46
	v_pk_fma_f32 v[102:103], v[102:103], v[142:143], v[140:141]
	v_lshlrev_b32_e32 v144, 16, v15
	v_and_b32_e32 v145, 0xffff0000, v15
	v_lshlrev_b32_e32 v152, 16, v47
	v_and_b32_e32 v153, 0xffff0000, v47
	v_pk_fma_f32 v[104:105], v[104:105], v[152:153], v[144:145]
	v_lshlrev_b32_e32 v140, 16, v16
	v_and_b32_e32 v141, 0xffff0000, v16
	v_lshlrev_b32_e32 v142, 16, v48
	v_and_b32_e32 v143, 0xffff0000, v48
	v_pk_fma_f32 v[98:99], v[98:99], v[142:143], v[140:141]
	v_lshlrev_b32_e32 v144, 16, v17
	v_and_b32_e32 v145, 0xffff0000, v17
	v_lshlrev_b32_e32 v152, 16, v49
	v_and_b32_e32 v153, 0xffff0000, v49
	v_pk_fma_f32 v[100:101], v[100:101], v[152:153], v[144:145]
	v_cvt_pk_bf16_f32 v101, v100, v101
	v_cvt_pk_bf16_f32 v100, v98, v99
	v_cvt_pk_bf16_f32 v98, v102, v103
	v_cvt_pk_bf16_f32 v99, v104, v105
	global_store_dwordx4 v[132:133], v[98:101], off offset:64
	s_waitcnt vmcnt(10)
	v_lshlrev_b32_e32 v140, 16, v18
	v_and_b32_e32 v141, 0xffff0000, v18
	v_lshlrev_b32_e32 v142, 16, v50
	v_and_b32_e32 v143, 0xffff0000, v50
	v_pk_fma_f32 v[94:95], v[94:95], v[142:143], v[140:141]
	v_lshlrev_b32_e32 v144, 16, v19
	v_and_b32_e32 v145, 0xffff0000, v19
	v_lshlrev_b32_e32 v152, 16, v51
	v_and_b32_e32 v153, 0xffff0000, v51
	v_pk_fma_f32 v[96:97], v[96:97], v[152:153], v[144:145]
	v_lshlrev_b32_e32 v140, 16, v20
	v_and_b32_e32 v141, 0xffff0000, v20
	v_lshlrev_b32_e32 v142, 16, v52
	v_and_b32_e32 v143, 0xffff0000, v52
	v_pk_fma_f32 v[90:91], v[90:91], v[142:143], v[140:141]
	v_lshlrev_b32_e32 v144, 16, v21
	v_and_b32_e32 v145, 0xffff0000, v21
	v_lshlrev_b32_e32 v152, 16, v53
	v_and_b32_e32 v153, 0xffff0000, v53
	v_pk_fma_f32 v[92:93], v[92:93], v[152:153], v[144:145]
	v_cvt_pk_bf16_f32 v93, v92, v93
	v_cvt_pk_bf16_f32 v92, v90, v91
	v_cvt_pk_bf16_f32 v90, v94, v95
	v_cvt_pk_bf16_f32 v91, v96, v97
	global_store_dwordx4 v[134:135], v[90:93], off
	s_waitcnt vmcnt(9)
	v_lshlrev_b32_e32 v140, 16, v22
	v_and_b32_e32 v141, 0xffff0000, v22
	v_lshlrev_b32_e32 v142, 16, v54
	v_and_b32_e32 v143, 0xffff0000, v54
	v_pk_fma_f32 v[86:87], v[86:87], v[142:143], v[140:141]
	v_lshlrev_b32_e32 v144, 16, v23
	v_and_b32_e32 v145, 0xffff0000, v23
	v_lshlrev_b32_e32 v152, 16, v55
	v_and_b32_e32 v153, 0xffff0000, v55
	v_pk_fma_f32 v[88:89], v[88:89], v[152:153], v[144:145]
	v_lshlrev_b32_e32 v140, 16, v24
	v_and_b32_e32 v141, 0xffff0000, v24
	v_lshlrev_b32_e32 v142, 16, v56
	v_and_b32_e32 v143, 0xffff0000, v56
	v_pk_fma_f32 v[82:83], v[82:83], v[142:143], v[140:141]
	v_lshlrev_b32_e32 v144, 16, v25
	v_and_b32_e32 v145, 0xffff0000, v25
	v_lshlrev_b32_e32 v152, 16, v57
	v_and_b32_e32 v153, 0xffff0000, v57
	v_pk_fma_f32 v[84:85], v[84:85], v[152:153], v[144:145]
	v_cvt_pk_bf16_f32 v85, v84, v85
	v_cvt_pk_bf16_f32 v84, v82, v83
	v_cvt_pk_bf16_f32 v82, v86, v87
	v_cvt_pk_bf16_f32 v83, v88, v89
	global_store_dwordx4 v[134:135], v[82:85], off offset:64
	s_waitcnt vmcnt(8)
	v_lshlrev_b32_e32 v140, 16, v26
	v_and_b32_e32 v141, 0xffff0000, v26
	v_lshlrev_b32_e32 v142, 16, v58
	v_and_b32_e32 v143, 0xffff0000, v58
	v_pk_fma_f32 v[78:79], v[78:79], v[142:143], v[140:141]
	v_lshlrev_b32_e32 v144, 16, v27
	v_and_b32_e32 v145, 0xffff0000, v27
	v_lshlrev_b32_e32 v152, 16, v59
	v_and_b32_e32 v153, 0xffff0000, v59
	v_pk_fma_f32 v[80:81], v[80:81], v[152:153], v[144:145]
	v_lshlrev_b32_e32 v140, 16, v28
	v_and_b32_e32 v141, 0xffff0000, v28
	v_lshlrev_b32_e32 v142, 16, v60
	v_and_b32_e32 v143, 0xffff0000, v60
	v_pk_fma_f32 v[74:75], v[74:75], v[142:143], v[140:141]
	v_lshlrev_b32_e32 v144, 16, v29
	v_and_b32_e32 v145, 0xffff0000, v29
	v_lshlrev_b32_e32 v152, 16, v61
	v_and_b32_e32 v153, 0xffff0000, v61
	v_pk_fma_f32 v[76:77], v[76:77], v[152:153], v[144:145]
	v_cvt_pk_bf16_f32 v77, v76, v77
	v_cvt_pk_bf16_f32 v76, v74, v75
	v_cvt_pk_bf16_f32 v74, v78, v79
	v_cvt_pk_bf16_f32 v75, v80, v81
	global_store_dwordx4 v[136:137], v[74:77], off
	s_waitcnt vmcnt(7)
	v_lshlrev_b32_e32 v140, 16, v30
	v_and_b32_e32 v141, 0xffff0000, v30
	v_lshlrev_b32_e32 v142, 16, v62
	v_and_b32_e32 v143, 0xffff0000, v62
	v_pk_fma_f32 v[66:67], v[66:67], v[142:143], v[140:141]
	v_lshlrev_b32_e32 v144, 16, v31
	v_and_b32_e32 v145, 0xffff0000, v31
	v_lshlrev_b32_e32 v152, 16, v63
	v_and_b32_e32 v153, 0xffff0000, v63
	v_pk_fma_f32 v[68:69], v[68:69], v[152:153], v[144:145]
	v_lshlrev_b32_e32 v140, 16, v32
	v_and_b32_e32 v141, 0xffff0000, v32
	v_lshlrev_b32_e32 v142, 16, v64
	v_and_b32_e32 v143, 0xffff0000, v64
	v_pk_fma_f32 v[70:71], v[70:71], v[142:143], v[140:141]
	v_lshlrev_b32_e32 v144, 16, v33
	v_and_b32_e32 v145, 0xffff0000, v33
	v_lshlrev_b32_e32 v152, 16, v65
	v_and_b32_e32 v153, 0xffff0000, v65
	v_pk_fma_f32 v[72:73], v[72:73], v[152:153], v[144:145]
	v_cvt_pk_bf16_f32 v66, v66, v67
	v_cvt_pk_bf16_f32 v67, v68, v69
	v_cvt_pk_bf16_f32 v68, v70, v71
	v_cvt_pk_bf16_f32 v69, v72, v73
	global_store_dwordx4 v[136:137], v[66:69], off offset:64
	s_branch .Lme_done
.Lme_s1:
	v_or_b32_e32 v0, s2, v147
	v_add_u32_e32 v140, s25, v146
	v_ashrrev_i32_e32 v141, 31, v140
	v_lshlrev_b64 v[140:141], 11, v[140:141]
	v_lshl_add_u64 v[140:141], v[0:1], 1, v[140:141]
	v_lshl_add_u64 v[130:131], v[140:141], 0, s[46:47]
	global_load_dwordx4 v[2:5], v[130:131], off
	global_load_dwordx4 v[6:9], v[130:131], off offset:64
	v_add_u32_e32 v140, s25, v148
	v_ashrrev_i32_e32 v141, 31, v140
	v_lshlrev_b64 v[140:141], 11, v[140:141]
	v_lshl_add_u64 v[140:141], v[0:1], 1, v[140:141]
	v_lshl_add_u64 v[132:133], v[140:141], 0, s[46:47]
	global_load_dwordx4 v[10:13], v[132:133], off
	global_load_dwordx4 v[14:17], v[132:133], off offset:64
	v_add_u32_e32 v140, s25, v149
	v_ashrrev_i32_e32 v141, 31, v140
	v_lshlrev_b64 v[140:141], 11, v[140:141]
	v_lshl_add_u64 v[140:141], v[0:1], 1, v[140:141]
	v_lshl_add_u64 v[134:135], v[140:141], 0, s[46:47]
	global_load_dwordx4 v[18:21], v[134:135], off
	global_load_dwordx4 v[22:25], v[134:135], off offset:64
	v_add_u32_e32 v140, s25, v150
	v_ashrrev_i32_e32 v141, 31, v140
	v_lshlrev_b64 v[140:141], 11, v[140:141]
	v_lshl_add_u64 v[140:141], v[0:1], 1, v[140:141]
	v_lshl_add_u64 v[136:137], v[140:141], 0, s[46:47]
	global_load_dwordx4 v[26:29], v[136:137], off
	global_load_dwordx4 v[30:33], v[136:137], off offset:64
	v_mul_f32_e32 v126, 0xbfb8aa3b, v126
	v_mul_f32_e32 v127, 0xbfb8aa3b, v127
	v_mul_f32_e32 v128, 0xbfb8aa3b, v128
	v_mul_f32_e32 v129, 0xbfb8aa3b, v129
	v_mul_f32_e32 v122, 0xbfb8aa3b, v122
	v_mul_f32_e32 v123, 0xbfb8aa3b, v123
	v_mul_f32_e32 v124, 0xbfb8aa3b, v124
	v_mul_f32_e32 v125, 0xbfb8aa3b, v125
	v_exp_f32_e32 v126, v126
	v_exp_f32_e32 v127, v127
	v_exp_f32_e32 v128, v128
	v_exp_f32_e32 v129, v129
	v_exp_f32_e32 v122, v122
	v_exp_f32_e32 v123, v123
	v_exp_f32_e32 v124, v124
	v_exp_f32_e32 v125, v125
	v_add_f32_e32 v126, 1.0, v126
	v_add_f32_e32 v127, 1.0, v127
	v_add_f32_e32 v128, 1.0, v128
	v_add_f32_e32 v129, 1.0, v129
	v_add_f32_e32 v122, 1.0, v122
	v_add_f32_e32 v123, 1.0, v123
	v_add_f32_e32 v124, 1.0, v124
	v_add_f32_e32 v125, 1.0, v125
	v_rcp_f32_e32 v126, v126
	v_rcp_f32_e32 v127, v127
	v_rcp_f32_e32 v128, v128
	v_rcp_f32_e32 v129, v129
	v_rcp_f32_e32 v122, v122
	v_rcp_f32_e32 v123, v123
	v_rcp_f32_e32 v124, v124
	v_rcp_f32_e32 v125, v125
	v_mul_f32_e32 v118, 0xbfb8aa3b, v118
	v_mul_f32_e32 v119, 0xbfb8aa3b, v119
	v_mul_f32_e32 v120, 0xbfb8aa3b, v120
	v_mul_f32_e32 v121, 0xbfb8aa3b, v121
	v_mul_f32_e32 v114, 0xbfb8aa3b, v114
	v_mul_f32_e32 v115, 0xbfb8aa3b, v115
	v_mul_f32_e32 v116, 0xbfb8aa3b, v116
	v_mul_f32_e32 v117, 0xbfb8aa3b, v117
	v_exp_f32_e32 v118, v118
	v_exp_f32_e32 v119, v119
	v_exp_f32_e32 v120, v120
	v_exp_f32_e32 v121, v121
	v_exp_f32_e32 v114, v114
	v_exp_f32_e32 v115, v115
	v_exp_f32_e32 v116, v116
	v_exp_f32_e32 v117, v117
	v_add_f32_e32 v118, 1.0, v118
	v_add_f32_e32 v119, 1.0, v119
	v_add_f32_e32 v120, 1.0, v120
	v_add_f32_e32 v121, 1.0, v121
	v_add_f32_e32 v114, 1.0, v114
	v_add_f32_e32 v115, 1.0, v115
	v_add_f32_e32 v116, 1.0, v116
	v_add_f32_e32 v117, 1.0, v117
	v_rcp_f32_e32 v118, v118
	v_rcp_f32_e32 v119, v119
	v_rcp_f32_e32 v120, v120
	v_rcp_f32_e32 v121, v121
	v_rcp_f32_e32 v114, v114
	v_rcp_f32_e32 v115, v115
	v_rcp_f32_e32 v116, v116
	v_rcp_f32_e32 v117, v117
	v_mul_f32_e32 v110, 0xbfb8aa3b, v110
	v_mul_f32_e32 v111, 0xbfb8aa3b, v111
	v_mul_f32_e32 v112, 0xbfb8aa3b, v112
	v_mul_f32_e32 v113, 0xbfb8aa3b, v113
	v_mul_f32_e32 v106, 0xbfb8aa3b, v106
	v_mul_f32_e32 v107, 0xbfb8aa3b, v107
	v_mul_f32_e32 v108, 0xbfb8aa3b, v108
	v_mul_f32_e32 v109, 0xbfb8aa3b, v109
	v_exp_f32_e32 v110, v110
	v_exp_f32_e32 v111, v111
	v_exp_f32_e32 v112, v112
	v_exp_f32_e32 v113, v113
	v_exp_f32_e32 v106, v106
	v_exp_f32_e32 v107, v107
	v_exp_f32_e32 v108, v108
	v_exp_f32_e32 v109, v109
	v_add_f32_e32 v110, 1.0, v110
	v_add_f32_e32 v111, 1.0, v111
	v_add_f32_e32 v112, 1.0, v112
	v_add_f32_e32 v113, 1.0, v113
	v_add_f32_e32 v106, 1.0, v106
	v_add_f32_e32 v107, 1.0, v107
	v_add_f32_e32 v108, 1.0, v108
	v_add_f32_e32 v109, 1.0, v109
	v_rcp_f32_e32 v110, v110
	v_rcp_f32_e32 v111, v111
	v_rcp_f32_e32 v112, v112
	v_rcp_f32_e32 v113, v113
	v_rcp_f32_e32 v106, v106
	v_rcp_f32_e32 v107, v107
	v_rcp_f32_e32 v108, v108
	v_rcp_f32_e32 v109, v109
	v_mul_f32_e32 v102, 0xbfb8aa3b, v102
	v_mul_f32_e32 v103, 0xbfb8aa3b, v103
	v_mul_f32_e32 v104, 0xbfb8aa3b, v104
	v_mul_f32_e32 v105, 0xbfb8aa3b, v105
	v_mul_f32_e32 v98, 0xbfb8aa3b, v98
	v_mul_f32_e32 v99, 0xbfb8aa3b, v99
	v_mul_f32_e32 v100, 0xbfb8aa3b, v100
	v_mul_f32_e32 v101, 0xbfb8aa3b, v101
	v_exp_f32_e32 v102, v102
	v_exp_f32_e32 v103, v103
	v_exp_f32_e32 v104, v104
	v_exp_f32_e32 v105, v105
	v_exp_f32_e32 v98, v98
	v_exp_f32_e32 v99, v99
	v_exp_f32_e32 v100, v100
	v_exp_f32_e32 v101, v101
	v_add_f32_e32 v102, 1.0, v102
	v_add_f32_e32 v103, 1.0, v103
	v_add_f32_e32 v104, 1.0, v104
	v_add_f32_e32 v105, 1.0, v105
	v_add_f32_e32 v98, 1.0, v98
	v_add_f32_e32 v99, 1.0, v99
	v_add_f32_e32 v100, 1.0, v100
	v_add_f32_e32 v101, 1.0, v101
	v_rcp_f32_e32 v102, v102
	v_rcp_f32_e32 v103, v103
	v_rcp_f32_e32 v104, v104
	v_rcp_f32_e32 v105, v105
	v_rcp_f32_e32 v98, v98
	v_rcp_f32_e32 v99, v99
	v_rcp_f32_e32 v100, v100
	v_rcp_f32_e32 v101, v101
	v_mul_f32_e32 v94, 0xbfb8aa3b, v94
	v_mul_f32_e32 v95, 0xbfb8aa3b, v95
	v_mul_f32_e32 v96, 0xbfb8aa3b, v96
	v_mul_f32_e32 v97, 0xbfb8aa3b, v97
	v_mul_f32_e32 v90, 0xbfb8aa3b, v90
	v_mul_f32_e32 v91, 0xbfb8aa3b, v91
	v_mul_f32_e32 v92, 0xbfb8aa3b, v92
	v_mul_f32_e32 v93, 0xbfb8aa3b, v93
	v_exp_f32_e32 v94, v94
	v_exp_f32_e32 v95, v95
	v_exp_f32_e32 v96, v96
	v_exp_f32_e32 v97, v97
	v_exp_f32_e32 v90, v90
	v_exp_f32_e32 v91, v91
	v_exp_f32_e32 v92, v92
	v_exp_f32_e32 v93, v93
	v_add_f32_e32 v94, 1.0, v94
	v_add_f32_e32 v95, 1.0, v95
	v_add_f32_e32 v96, 1.0, v96
	v_add_f32_e32 v97, 1.0, v97
	v_add_f32_e32 v90, 1.0, v90
	v_add_f32_e32 v91, 1.0, v91
	v_add_f32_e32 v92, 1.0, v92
	v_add_f32_e32 v93, 1.0, v93
	v_rcp_f32_e32 v94, v94
	v_rcp_f32_e32 v95, v95
	v_rcp_f32_e32 v96, v96
	v_rcp_f32_e32 v97, v97
	v_rcp_f32_e32 v90, v90
	v_rcp_f32_e32 v91, v91
	v_rcp_f32_e32 v92, v92
	v_rcp_f32_e32 v93, v93
	v_mul_f32_e32 v86, 0xbfb8aa3b, v86
	v_mul_f32_e32 v87, 0xbfb8aa3b, v87
	v_mul_f32_e32 v88, 0xbfb8aa3b, v88
	v_mul_f32_e32 v89, 0xbfb8aa3b, v89
	v_mul_f32_e32 v82, 0xbfb8aa3b, v82
	v_mul_f32_e32 v83, 0xbfb8aa3b, v83
	v_mul_f32_e32 v84, 0xbfb8aa3b, v84
	v_mul_f32_e32 v85, 0xbfb8aa3b, v85
	v_exp_f32_e32 v86, v86
	v_exp_f32_e32 v87, v87
	v_exp_f32_e32 v88, v88
	v_exp_f32_e32 v89, v89
	v_exp_f32_e32 v82, v82
	v_exp_f32_e32 v83, v83
	v_exp_f32_e32 v84, v84
	v_exp_f32_e32 v85, v85
	v_add_f32_e32 v86, 1.0, v86
	v_add_f32_e32 v87, 1.0, v87
	v_add_f32_e32 v88, 1.0, v88
	v_add_f32_e32 v89, 1.0, v89
	v_add_f32_e32 v82, 1.0, v82
	v_add_f32_e32 v83, 1.0, v83
	v_add_f32_e32 v84, 1.0, v84
	v_add_f32_e32 v85, 1.0, v85
	v_rcp_f32_e32 v86, v86
	v_rcp_f32_e32 v87, v87
	v_rcp_f32_e32 v88, v88
	v_rcp_f32_e32 v89, v89
	v_rcp_f32_e32 v82, v82
	v_rcp_f32_e32 v83, v83
	v_rcp_f32_e32 v84, v84
	v_rcp_f32_e32 v85, v85
	v_mul_f32_e32 v78, 0xbfb8aa3b, v78
	v_mul_f32_e32 v79, 0xbfb8aa3b, v79
	v_mul_f32_e32 v80, 0xbfb8aa3b, v80
	v_mul_f32_e32 v81, 0xbfb8aa3b, v81
	v_mul_f32_e32 v74, 0xbfb8aa3b, v74
	v_mul_f32_e32 v75, 0xbfb8aa3b, v75
	v_mul_f32_e32 v76, 0xbfb8aa3b, v76
	v_mul_f32_e32 v77, 0xbfb8aa3b, v77
	v_exp_f32_e32 v78, v78
	v_exp_f32_e32 v79, v79
	v_exp_f32_e32 v80, v80
	v_exp_f32_e32 v81, v81
	v_exp_f32_e32 v74, v74
	v_exp_f32_e32 v75, v75
	v_exp_f32_e32 v76, v76
	v_exp_f32_e32 v77, v77
	v_add_f32_e32 v78, 1.0, v78
	v_add_f32_e32 v79, 1.0, v79
	v_add_f32_e32 v80, 1.0, v80
	v_add_f32_e32 v81, 1.0, v81
	v_add_f32_e32 v74, 1.0, v74
	v_add_f32_e32 v75, 1.0, v75
	v_add_f32_e32 v76, 1.0, v76
	v_add_f32_e32 v77, 1.0, v77
	v_rcp_f32_e32 v78, v78
	v_rcp_f32_e32 v79, v79
	v_rcp_f32_e32 v80, v80
	v_rcp_f32_e32 v81, v81
	v_rcp_f32_e32 v74, v74
	v_rcp_f32_e32 v75, v75
	v_rcp_f32_e32 v76, v76
	v_rcp_f32_e32 v77, v77
	v_mul_f32_e32 v66, 0xbfb8aa3b, v66
	v_mul_f32_e32 v67, 0xbfb8aa3b, v67
	v_mul_f32_e32 v68, 0xbfb8aa3b, v68
	v_mul_f32_e32 v69, 0xbfb8aa3b, v69
	v_mul_f32_e32 v70, 0xbfb8aa3b, v70
	v_mul_f32_e32 v71, 0xbfb8aa3b, v71
	v_mul_f32_e32 v72, 0xbfb8aa3b, v72
	v_mul_f32_e32 v73, 0xbfb8aa3b, v73
	v_exp_f32_e32 v66, v66
	v_exp_f32_e32 v67, v67
	v_exp_f32_e32 v68, v68
	v_exp_f32_e32 v69, v69
	v_exp_f32_e32 v70, v70
	v_exp_f32_e32 v71, v71
	v_exp_f32_e32 v72, v72
	v_exp_f32_e32 v73, v73
	v_add_f32_e32 v66, 1.0, v66
	v_add_f32_e32 v67, 1.0, v67
	v_add_f32_e32 v68, 1.0, v68
	v_add_f32_e32 v69, 1.0, v69
	v_add_f32_e32 v70, 1.0, v70
	v_add_f32_e32 v71, 1.0, v71
	v_add_f32_e32 v72, 1.0, v72
	v_add_f32_e32 v73, 1.0, v73
	v_rcp_f32_e32 v66, v66
	v_rcp_f32_e32 v67, v67
	v_rcp_f32_e32 v68, v68
	v_rcp_f32_e32 v69, v69
	v_rcp_f32_e32 v70, v70
	v_rcp_f32_e32 v71, v71
	v_rcp_f32_e32 v72, v72
	v_rcp_f32_e32 v73, v73
	s_nop 0
	s_waitcnt vmcnt(7)
	v_lshlrev_b32_e32 v34, 16, v2
	v_and_b32_e32 v35, 0xffff0000, v2
	v_lshlrev_b32_e32 v36, 16, v3
	v_and_b32_e32 v37, 0xffff0000, v3
	v_lshlrev_b32_e32 v38, 16, v4
	v_and_b32_e32 v39, 0xffff0000, v4
	v_lshlrev_b32_e32 v40, 16, v5
	v_and_b32_e32 v41, 0xffff0000, v5
	v_pk_mul_f32 v[126:127], v[126:127], v[34:35]
	v_pk_mul_f32 v[128:129], v[128:129], v[36:37]
	v_pk_mul_f32 v[122:123], v[122:123], v[38:39]
	v_pk_mul_f32 v[124:125], v[124:125], v[40:41]
	v_cvt_pk_bf16_f32 v125, v124, v125
	v_cvt_pk_bf16_f32 v124, v122, v123
	v_cvt_pk_bf16_f32 v122, v126, v127
	v_cvt_pk_bf16_f32 v123, v128, v129
	global_store_dwordx4 v[130:131], v[122:125], off
	s_waitcnt vmcnt(7)
	v_lshlrev_b32_e32 v34, 16, v6
	v_and_b32_e32 v35, 0xffff0000, v6
	v_lshlrev_b32_e32 v36, 16, v7
	v_and_b32_e32 v37, 0xffff0000, v7
	v_lshlrev_b32_e32 v38, 16, v8
	v_and_b32_e32 v39, 0xffff0000, v8
	v_lshlrev_b32_e32 v40, 16, v9
	v_and_b32_e32 v41, 0xffff0000, v9
	v_pk_mul_f32 v[118:119], v[118:119], v[34:35]
	v_pk_mul_f32 v[120:121], v[120:121], v[36:37]
	v_pk_mul_f32 v[114:115], v[114:115], v[38:39]
	v_pk_mul_f32 v[116:117], v[116:117], v[40:41]
	v_cvt_pk_bf16_f32 v117, v116, v117
	v_cvt_pk_bf16_f32 v116, v114, v115
	v_cvt_pk_bf16_f32 v114, v118, v119
	v_cvt_pk_bf16_f32 v115, v120, v121
	global_store_dwordx4 v[130:131], v[114:117], off offset:64
	s_waitcnt vmcnt(7)
	v_lshlrev_b32_e32 v34, 16, v10
	v_and_b32_e32 v35, 0xffff0000, v10
	v_lshlrev_b32_e32 v36, 16, v11
	v_and_b32_e32 v37, 0xffff0000, v11
	v_lshlrev_b32_e32 v38, 16, v12
	v_and_b32_e32 v39, 0xffff0000, v12
	v_lshlrev_b32_e32 v40, 16, v13
	v_and_b32_e32 v41, 0xffff0000, v13
	v_pk_mul_f32 v[110:111], v[110:111], v[34:35]
	v_pk_mul_f32 v[112:113], v[112:113], v[36:37]
	v_pk_mul_f32 v[106:107], v[106:107], v[38:39]
	v_pk_mul_f32 v[108:109], v[108:109], v[40:41]
	v_cvt_pk_bf16_f32 v109, v108, v109
	v_cvt_pk_bf16_f32 v108, v106, v107
	v_cvt_pk_bf16_f32 v106, v110, v111
	v_cvt_pk_bf16_f32 v107, v112, v113
	global_store_dwordx4 v[132:133], v[106:109], off
	s_waitcnt vmcnt(7)
	v_lshlrev_b32_e32 v34, 16, v14
	v_and_b32_e32 v35, 0xffff0000, v14
	v_lshlrev_b32_e32 v36, 16, v15
	v_and_b32_e32 v37, 0xffff0000, v15
	v_lshlrev_b32_e32 v38, 16, v16
	v_and_b32_e32 v39, 0xffff0000, v16
	v_lshlrev_b32_e32 v40, 16, v17
	v_and_b32_e32 v41, 0xffff0000, v17
	v_pk_mul_f32 v[102:103], v[102:103], v[34:35]
	v_pk_mul_f32 v[104:105], v[104:105], v[36:37]
	v_pk_mul_f32 v[98:99], v[98:99], v[38:39]
	v_pk_mul_f32 v[100:101], v[100:101], v[40:41]
	v_cvt_pk_bf16_f32 v101, v100, v101
	v_cvt_pk_bf16_f32 v100, v98, v99
	v_cvt_pk_bf16_f32 v98, v102, v103
	v_cvt_pk_bf16_f32 v99, v104, v105
	global_store_dwordx4 v[132:133], v[98:101], off offset:64
	s_waitcnt vmcnt(7)
	v_lshlrev_b32_e32 v34, 16, v18
	v_and_b32_e32 v35, 0xffff0000, v18
	v_lshlrev_b32_e32 v36, 16, v19
	v_and_b32_e32 v37, 0xffff0000, v19
	v_lshlrev_b32_e32 v38, 16, v20
	v_and_b32_e32 v39, 0xffff0000, v20
	v_lshlrev_b32_e32 v40, 16, v21
	v_and_b32_e32 v41, 0xffff0000, v21
	v_pk_mul_f32 v[94:95], v[94:95], v[34:35]
	v_pk_mul_f32 v[96:97], v[96:97], v[36:37]
	v_pk_mul_f32 v[90:91], v[90:91], v[38:39]
	v_pk_mul_f32 v[92:93], v[92:93], v[40:41]
	v_cvt_pk_bf16_f32 v93, v92, v93
	v_cvt_pk_bf16_f32 v92, v90, v91
	v_cvt_pk_bf16_f32 v90, v94, v95
	v_cvt_pk_bf16_f32 v91, v96, v97
	global_store_dwordx4 v[134:135], v[90:93], off
	s_waitcnt vmcnt(7)
	v_lshlrev_b32_e32 v34, 16, v22
	v_and_b32_e32 v35, 0xffff0000, v22
	v_lshlrev_b32_e32 v36, 16, v23
	v_and_b32_e32 v37, 0xffff0000, v23
	v_lshlrev_b32_e32 v38, 16, v24
	v_and_b32_e32 v39, 0xffff0000, v24
	v_lshlrev_b32_e32 v40, 16, v25
	v_and_b32_e32 v41, 0xffff0000, v25
	v_pk_mul_f32 v[86:87], v[86:87], v[34:35]
	v_pk_mul_f32 v[88:89], v[88:89], v[36:37]
	v_pk_mul_f32 v[82:83], v[82:83], v[38:39]
	v_pk_mul_f32 v[84:85], v[84:85], v[40:41]
	v_cvt_pk_bf16_f32 v85, v84, v85
	v_cvt_pk_bf16_f32 v84, v82, v83
	v_cvt_pk_bf16_f32 v82, v86, v87
	v_cvt_pk_bf16_f32 v83, v88, v89
	global_store_dwordx4 v[134:135], v[82:85], off offset:64
	s_waitcnt vmcnt(7)
	v_lshlrev_b32_e32 v34, 16, v26
	v_and_b32_e32 v35, 0xffff0000, v26
	v_lshlrev_b32_e32 v36, 16, v27
	v_and_b32_e32 v37, 0xffff0000, v27
	v_lshlrev_b32_e32 v38, 16, v28
	v_and_b32_e32 v39, 0xffff0000, v28
	v_lshlrev_b32_e32 v40, 16, v29
	v_and_b32_e32 v41, 0xffff0000, v29
	v_pk_mul_f32 v[78:79], v[78:79], v[34:35]
	v_pk_mul_f32 v[80:81], v[80:81], v[36:37]
	v_pk_mul_f32 v[74:75], v[74:75], v[38:39]
	v_pk_mul_f32 v[76:77], v[76:77], v[40:41]
	v_cvt_pk_bf16_f32 v77, v76, v77
	v_cvt_pk_bf16_f32 v76, v74, v75
	v_cvt_pk_bf16_f32 v74, v78, v79
	v_cvt_pk_bf16_f32 v75, v80, v81
	global_store_dwordx4 v[136:137], v[74:77], off
	s_waitcnt vmcnt(7)
	v_lshlrev_b32_e32 v34, 16, v30
	v_and_b32_e32 v35, 0xffff0000, v30
	v_lshlrev_b32_e32 v36, 16, v31
	v_and_b32_e32 v37, 0xffff0000, v31
	v_lshlrev_b32_e32 v38, 16, v32
	v_and_b32_e32 v39, 0xffff0000, v32
	v_lshlrev_b32_e32 v40, 16, v33
	v_and_b32_e32 v41, 0xffff0000, v33
	v_pk_mul_f32 v[66:67], v[66:67], v[34:35]
	v_pk_mul_f32 v[68:69], v[68:69], v[36:37]
	v_pk_mul_f32 v[70:71], v[70:71], v[38:39]
	v_pk_mul_f32 v[72:73], v[72:73], v[40:41]
	v_cvt_pk_bf16_f32 v66, v66, v67
	v_cvt_pk_bf16_f32 v67, v68, v69
	v_cvt_pk_bf16_f32 v68, v70, v71
	v_cvt_pk_bf16_f32 v69, v72, v73
	global_store_dwordx4 v[136:137], v[66:69], off offset:64
	s_branch .Lme_done
.Lme_s0:
	v_or_b32_e32 v0, s2, v147
	v_add_u32_e32 v140, s25, v146
	v_ashrrev_i32_e32 v141, 31, v140
	v_lshlrev_b64 v[140:141], 11, v[140:141]
	v_lshl_add_u64 v[140:141], v[0:1], 1, v[140:141]
	v_lshl_add_u64 v[130:131], v[140:141], 0, s[46:47]
	v_add_u32_e32 v140, s25, v148
	v_ashrrev_i32_e32 v141, 31, v140
	v_lshlrev_b64 v[140:141], 11, v[140:141]
	v_lshl_add_u64 v[140:141], v[0:1], 1, v[140:141]
	v_lshl_add_u64 v[132:133], v[140:141], 0, s[46:47]
	v_add_u32_e32 v140, s25, v149
	v_ashrrev_i32_e32 v141, 31, v140
	v_lshlrev_b64 v[140:141], 11, v[140:141]
	v_lshl_add_u64 v[140:141], v[0:1], 1, v[140:141]
	v_lshl_add_u64 v[134:135], v[140:141], 0, s[46:47]
	v_add_u32_e32 v140, s25, v150
	v_ashrrev_i32_e32 v141, 31, v140
	v_lshlrev_b64 v[140:141], 11, v[140:141]
	v_lshl_add_u64 v[140:141], v[0:1], 1, v[140:141]
	v_lshl_add_u64 v[136:137], v[140:141], 0, s[46:47]
	v_cvt_pk_bf16_f32 v125, v124, v125
	v_cvt_pk_bf16_f32 v124, v122, v123
	v_cvt_pk_bf16_f32 v122, v126, v127
	v_cvt_pk_bf16_f32 v123, v128, v129
	global_store_dwordx4 v[130:131], v[122:125], off
	v_cvt_pk_bf16_f32 v117, v116, v117
	v_cvt_pk_bf16_f32 v116, v114, v115
	v_cvt_pk_bf16_f32 v114, v118, v119
	v_cvt_pk_bf16_f32 v115, v120, v121
	global_store_dwordx4 v[130:131], v[114:117], off offset:64
	v_cvt_pk_bf16_f32 v109, v108, v109
	v_cvt_pk_bf16_f32 v108, v106, v107
	v_cvt_pk_bf16_f32 v106, v110, v111
	v_cvt_pk_bf16_f32 v107, v112, v113
	global_store_dwordx4 v[132:133], v[106:109], off
	v_cvt_pk_bf16_f32 v101, v100, v101
	v_cvt_pk_bf16_f32 v100, v98, v99
	v_cvt_pk_bf16_f32 v98, v102, v103
	v_cvt_pk_bf16_f32 v99, v104, v105
	global_store_dwordx4 v[132:133], v[98:101], off offset:64
	v_cvt_pk_bf16_f32 v93, v92, v93
	v_cvt_pk_bf16_f32 v92, v90, v91
	v_cvt_pk_bf16_f32 v90, v94, v95
	v_cvt_pk_bf16_f32 v91, v96, v97
	global_store_dwordx4 v[134:135], v[90:93], off
	v_cvt_pk_bf16_f32 v85, v84, v85
	v_cvt_pk_bf16_f32 v84, v82, v83
	v_cvt_pk_bf16_f32 v82, v86, v87
	v_cvt_pk_bf16_f32 v83, v88, v89
	global_store_dwordx4 v[134:135], v[82:85], off offset:64
	v_cvt_pk_bf16_f32 v77, v76, v77
	v_cvt_pk_bf16_f32 v76, v74, v75
	v_cvt_pk_bf16_f32 v74, v78, v79
	v_cvt_pk_bf16_f32 v75, v80, v81
	global_store_dwordx4 v[136:137], v[74:77], off
	v_cvt_pk_bf16_f32 v66, v66, v67
	v_cvt_pk_bf16_f32 v67, v68, v69
	v_cvt_pk_bf16_f32 v68, v70, v71
	v_cvt_pk_bf16_f32 v69, v72, v73
	global_store_dwordx4 v[136:137], v[66:69], off offset:64
.Lme_done:
	s_andn2_b64 vcc, exec, s[50:51]
	s_mov_b64 s[50:51], -1
	s_cbranch_vccnz .LBB0_235
	s_and_b64 vcc, exec, s[48:49]
	s_cbranch_vccz .LBB0_309
	v_mov_b32_e32 v0, v169
	s_lshl_b32 s2, s10, 10
	v_mov_b32_e32 v67, v169
	s_or_b32 s2, s2, s15
	v_lshrrev_b32_e32 v66, 3, v0
	v_lshlrev_b32_e32 v0, 3, v0
	s_add_i32 s2, s2, 0x3ffc00
	v_lshrrev_b32_e32 v69, 3, v67
	v_lshlrev_b32_e32 v67, 3, v67
	v_add_u32_e32 v66, s14, v66
	v_and_b32_e32 v0, 56, v0
	v_add_u32_e32 v69, s2, v69
	v_and_b32_e32 v67, 56, v67
	v_lshl_or_b32 v0, v66, 10, v0
	v_lshl_or_b32 v78, v69, 10, v67
	v_add_u32_e32 v70, 0x8000, v0
	v_add_u32_e32 v68, 0x10000, v0
	v_add_u32_e32 v66, 0x18000, v0
	v_add_u32_e32 v76, 0x8000, v78
	v_add_u32_e32 v74, 0x10000, v78
	v_add_u32_e32 v72, 0x18000, v78
	s_mov_b64 s[28:29], 0
	s_branch .LBB0_310
